# v82 + qatomic: deferred weight-copy tile queue issues its ticket atomic at the top of the turn so the round trip overlaps the loop-top drain
# baseline (speedup 1.0000x reference)
.LBB0_2010:
	s_and_saveexec_b64 s[100:101], s[36:37]
	s_cbranch_execz .Lmy_q_noat
	v_mov_b32_e32 v148, 3
	global_atomic_add v148, v181, v148, s[2:3] sc0
.Lmy_q_noat:
	s_mov_b64 exec, s[100:101]
	s_waitcnt vmcnt(1)
	v_mul_f32_e32 v104, v2, v108
	v_mul_f32_e32 v105, v3, v108
	v_cvt_pk_bf16_f32 v104, v104, v105
	ds_write_b32 v127, v104
	v_mul_f32_e32 v104, v4, v108
	v_mul_f32_e32 v105, v5, v108
	v_cvt_pk_bf16_f32 v104, v104, v105
	ds_write_b32 v127, v104 offset:4
	s_waitcnt vmcnt(0)
	v_mul_f32_e32 v104, v6, v109
	v_mul_f32_e32 v105, v7, v109
	v_cvt_pk_bf16_f32 v104, v104, v105
	ds_write_b32 v127, v104 offset:4160
	v_mul_f32_e32 v104, v8, v109
	v_mul_f32_e32 v105, v9, v109
	v_cvt_pk_bf16_f32 v104, v104, v105
	ds_write_b32 v127, v104 offset:4164
	v_mul_f32_e32 v104, v10, v101
	v_mul_f32_e32 v105, v11, v101
	v_cvt_pk_bf16_f32 v104, v104, v105
	ds_write_b32 v127, v104 offset:8320
	v_mul_f32_e32 v104, v12, v101
	v_mul_f32_e32 v105, v13, v101
	v_cvt_pk_bf16_f32 v104, v104, v105
	ds_write_b32 v127, v104 offset:8324
	v_mul_f32_e32 v104, v14, v110
	v_mul_f32_e32 v105, v15, v110
	v_cvt_pk_bf16_f32 v104, v104, v105
	ds_write_b32 v127, v104 offset:12480
	v_mul_f32_e32 v104, v16, v110
	v_mul_f32_e32 v105, v17, v110
	v_cvt_pk_bf16_f32 v104, v104, v105
	ds_write_b32 v127, v104 offset:12484
	v_mul_f32_e32 v104, v18, v112
	v_mul_f32_e32 v105, v19, v112
	v_cvt_pk_bf16_f32 v104, v104, v105
	ds_write_b32 v127, v104 offset:16640
	v_mul_f32_e32 v104, v20, v112
	v_mul_f32_e32 v105, v21, v112
	v_cvt_pk_bf16_f32 v104, v104, v105
	ds_write_b32 v127, v104 offset:16644
	v_mul_f32_e32 v104, v26, v113
	v_mul_f32_e32 v105, v27, v113
	v_cvt_pk_bf16_f32 v104, v104, v105
	ds_write_b32 v127, v104 offset:20800
	v_mul_f32_e32 v104, v28, v113
	v_mul_f32_e32 v105, v29, v113
	v_cvt_pk_bf16_f32 v104, v104, v105
	ds_write_b32 v127, v104 offset:20804
	v_mul_f32_e32 v104, v30, v111
	v_mul_f32_e32 v105, v31, v111
	v_cvt_pk_bf16_f32 v104, v104, v105
	ds_write_b32 v127, v104 offset:24960
	v_mul_f32_e32 v104, v32, v111
	v_mul_f32_e32 v105, v33, v111
	v_cvt_pk_bf16_f32 v104, v104, v105
	ds_write_b32 v127, v104 offset:24964
	v_mul_f32_e32 v104, v22, v114
	v_mul_f32_e32 v105, v23, v114
	v_cvt_pk_bf16_f32 v104, v104, v105
	ds_write_b32 v127, v104 offset:29120
	v_mul_f32_e32 v104, v24, v114
	v_mul_f32_e32 v105, v25, v114
	v_cvt_pk_bf16_f32 v104, v104, v105
	ds_write_b32 v127, v104 offset:29124
	s_and_saveexec_b64 s[38:39], s[36:37]
	s_cbranch_execz .LBB0_2014
	s_mov_b64 s[42:43], exec
	v_mbcnt_lo_u32_b32 v104, s42, 0
	v_mbcnt_hi_u32_b32 v104, s43, v104
	v_cmp_eq_u32_e32 vcc, 0, v104
	s_and_saveexec_b64 s[40:41], vcc
	s_cbranch_execz .LBB0_2013
	s_bcnt1_i32_b64 s7, s[42:43]
	s_mul_i32 s7, s7, 3
	v_mov_b32_e32 v105, s7
	v_mov_b32_e32 v105, v148
